# plus: dead high-part mad + shuttle moves removed from SwiGLU epilogue store addressing
# speedup vs baseline: 1.0032x; 1.0032x over previous
.LBB0_127:
	s_waitcnt lgkmcnt(0)
	v_mul_f32_e32 v130, 0xbfb8aa3b, v170
	v_mul_f32_e32 v131, v170, v170
	v_pk_mul_f32 v[168:169], v[126:127], v[130:131] op_sel_hi:[1,0]
	v_rcp_f32_e32 v134, v131
	v_pk_mul_f32 v[182:183], v[124:125], v[130:131] op_sel_hi:[1,0]
	v_exp_f32_e32 v168, v168
	v_exp_f32_e32 v169, v169
	v_pk_mul_f32 v[122:123], v[126:127], v[122:123]
	v_pk_mul_f32 v[126:127], v[116:117], v[130:131] op_sel_hi:[1,0]
	v_exp_f32_e32 v182, v182
	v_exp_f32_e32 v183, v183
	v_exp_f32_e32 v126, v126
	v_exp_f32_e32 v127, v127
	v_pk_mul_f32 v[120:121], v[124:125], v[120:121]
	v_pk_mul_f32 v[124:125], v[118:119], v[130:131] op_sel_hi:[1,0]
	v_pk_fma_f32 v[168:169], v[168:169], v[134:135], v[134:135] op_sel_hi:[1,0,0]
	v_exp_f32_e32 v124, v124
	v_exp_f32_e32 v125, v125
	v_pk_fma_f32 v[182:183], v[182:183], v[134:135], v[134:135] op_sel_hi:[1,0,0]
	v_rcp_f32_e32 v168, v168
	v_rcp_f32_e32 v169, v169
	v_pk_fma_f32 v[126:127], v[126:127], v[134:135], v[134:135] op_sel_hi:[1,0,0]
	v_rcp_f32_e32 v182, v182
	v_rcp_f32_e32 v183, v183
	v_rcp_f32_e32 v126, v126
	v_rcp_f32_e32 v127, v127
	v_pk_fma_f32 v[124:125], v[124:125], v[134:135], v[134:135] op_sel_hi:[1,0,0]
	v_pk_mul_f32 v[122:123], v[122:123], v[168:169]
	v_rcp_f32_e32 v124, v124
	v_rcp_f32_e32 v125, v125
	v_pk_mul_f32 v[112:113], v[116:117], v[112:113]
	v_pk_mul_f32 v[120:121], v[120:121], v[182:183]
	v_pk_mul_f32 v[112:113], v[112:113], v[126:127]
	v_cvt_pk_bf16_f32 v116, v120, v121
	v_cvt_pk_bf16_f32 v117, v122, v123
	v_mul_f32_e32 v122, 0xbfb8aa3b, v171
	v_mul_f32_e32 v123, v171, v171
	v_pk_mul_f32 v[114:115], v[118:119], v[114:115]
	v_cvt_pk_bf16_f32 v118, v112, v113
	v_mov_b64_e32 v[112:113], s[64:65]
	v_pk_mul_f32 v[126:127], v[110:111], v[122:123] op_sel_hi:[1,0]
	v_pk_mul_f32 v[130:131], v[108:109], v[122:123] op_sel_hi:[1,0]
	v_pk_mul_f32 v[106:107], v[110:111], v[106:107]
	v_pk_mul_f32 v[104:105], v[108:109], v[104:105]
	v_pk_mul_f32 v[108:109], v[102:103], v[122:123] op_sel_hi:[1,0]
	v_pk_mul_f32 v[110:111], v[100:101], v[122:123] op_sel_hi:[1,0]
	v_pk_mul_f32 v[114:115], v[114:115], v[124:125]
	v_mad_u64_u32 v[120:121], s[52:53], v164, s27, v[112:113]
	v_rcp_f32_e32 v124, v123
	v_exp_f32_e32 v110, v110
	v_exp_f32_e32 v108, v108
	v_exp_f32_e32 v109, v109
	v_exp_f32_e32 v111, v111
	v_lshl_or_b32 v184, s54, 7, v177
	v_cvt_pk_bf16_f32 v119, v114, v115
	v_exp_f32_e32 v130, v130
	v_exp_f32_e32 v126, v126
	v_exp_f32_e32 v127, v127
	v_exp_f32_e32 v131, v131
	v_ashrrev_i32_e32 v185, 31, v184
	v_lshlrev_b64 v[114:115], 1, v[184:185]
	v_lshl_add_u64 v[120:121], v[120:121], 0, v[114:115]
	v_pk_fma_f32 v[108:109], v[108:109], v[124:125], v[124:125] op_sel_hi:[1,0,0]
	v_pk_fma_f32 v[110:111], v[110:111], v[124:125], v[124:125] op_sel_hi:[1,0,0]
	global_store_dwordx4 v[120:121], v[116:119], off
	v_rcp_f32_e32 v110, v110
	v_rcp_f32_e32 v108, v108
	v_pk_fma_f32 v[116:117], v[126:127], v[124:125], v[124:125] op_sel_hi:[1,0,0]
	v_pk_fma_f32 v[118:119], v[130:131], v[124:125], v[124:125] op_sel_hi:[1,0,0]
	v_rcp_f32_e32 v109, v109
	v_rcp_f32_e32 v111, v111
	v_rcp_f32_e32 v118, v118
	v_rcp_f32_e32 v119, v119
	v_rcp_f32_e32 v116, v116
	v_rcp_f32_e32 v117, v117
	v_pk_mul_f32 v[98:99], v[102:103], v[98:99]
	v_pk_mul_f32 v[96:97], v[100:101], v[96:97]
	v_pk_mul_f32 v[100:101], v[98:99], v[108:109]
	v_pk_mul_f32 v[98:99], v[96:97], v[110:111]
	v_pk_mul_f32 v[106:107], v[106:107], v[116:117]
	v_pk_mul_f32 v[104:105], v[104:105], v[118:119]
	v_pk_mul_f32 v[90:91], v[94:95], v[90:91]
	v_cvt_pk_bf16_f32 v96, v104, v105
	v_cvt_pk_bf16_f32 v97, v106, v107
	v_cvt_pk_bf16_f32 v98, v98, v99
	v_cvt_pk_bf16_f32 v99, v100, v101
	v_mad_u64_u32 v[100:101], s[52:53], v160, s27, v[112:113]
	v_mul_f32_e32 v102, 0xbfb8aa3b, v166
	v_mul_f32_e32 v103, v166, v166
	v_pk_mul_f32 v[106:107], v[94:95], v[102:103] op_sel_hi:[1,0]
	v_pk_mul_f32 v[108:109], v[92:93], v[102:103] op_sel_hi:[1,0]
	v_pk_mul_f32 v[88:89], v[92:93], v[88:89]
	v_pk_mul_f32 v[92:93], v[86:87], v[102:103] op_sel_hi:[1,0]
	v_pk_mul_f32 v[94:95], v[84:85], v[102:103] op_sel_hi:[1,0]
	v_rcp_f32_e32 v104, v103
	v_exp_f32_e32 v94, v94
	v_exp_f32_e32 v92, v92
	v_exp_f32_e32 v93, v93
	v_exp_f32_e32 v95, v95
	v_exp_f32_e32 v108, v108
	v_exp_f32_e32 v106, v106
	v_exp_f32_e32 v107, v107
	v_exp_f32_e32 v109, v109
	v_lshl_add_u64 v[100:101], v[100:101], 0, v[114:115]
	v_pk_fma_f32 v[92:93], v[92:93], v[104:105], v[104:105] op_sel_hi:[1,0,0]
	v_pk_fma_f32 v[94:95], v[94:95], v[104:105], v[104:105] op_sel_hi:[1,0,0]
	global_store_dwordx4 v[100:101], v[96:99], off
	v_rcp_f32_e32 v94, v94
	v_rcp_f32_e32 v92, v92
	v_pk_fma_f32 v[96:97], v[106:107], v[104:105], v[104:105] op_sel_hi:[1,0,0]
	v_pk_fma_f32 v[98:99], v[108:109], v[104:105], v[104:105] op_sel_hi:[1,0,0]
	v_rcp_f32_e32 v93, v93
	v_rcp_f32_e32 v95, v95
	v_rcp_f32_e32 v98, v98
	v_rcp_f32_e32 v99, v99
	v_rcp_f32_e32 v96, v96
	v_rcp_f32_e32 v97, v97
	v_pk_mul_f32 v[82:83], v[86:87], v[82:83]
	v_pk_mul_f32 v[80:81], v[84:85], v[80:81]
	v_pk_mul_f32 v[84:85], v[82:83], v[92:93]
	v_pk_mul_f32 v[82:83], v[80:81], v[94:95]
	v_pk_mul_f32 v[90:91], v[90:91], v[96:97]
	v_pk_mul_f32 v[88:89], v[88:89], v[98:99]
	v_pk_mul_f32 v[74:75], v[78:79], v[74:75]
	v_cvt_pk_bf16_f32 v80, v88, v89
	v_cvt_pk_bf16_f32 v81, v90, v91
	v_cvt_pk_bf16_f32 v82, v82, v83
	v_cvt_pk_bf16_f32 v83, v84, v85
	v_mad_u64_u32 v[84:85], s[52:53], v158, s27, v[112:113]
	v_mul_f32_e32 v86, 0xbfb8aa3b, v167
	v_mul_f32_e32 v87, v167, v167
	v_pk_mul_f32 v[90:91], v[78:79], v[86:87] op_sel_hi:[1,0]
	v_pk_mul_f32 v[92:93], v[76:77], v[86:87] op_sel_hi:[1,0]
	v_pk_mul_f32 v[72:73], v[76:77], v[72:73]
	v_pk_mul_f32 v[76:77], v[70:71], v[86:87] op_sel_hi:[1,0]
	v_pk_mul_f32 v[78:79], v[68:69], v[86:87] op_sel_hi:[1,0]
	v_rcp_f32_e32 v88, v87
	v_exp_f32_e32 v78, v78
	v_exp_f32_e32 v76, v76
	v_exp_f32_e32 v77, v77
	v_exp_f32_e32 v79, v79
	v_exp_f32_e32 v92, v92
	v_exp_f32_e32 v90, v90
	v_exp_f32_e32 v91, v91
	v_exp_f32_e32 v93, v93
	v_lshl_add_u64 v[84:85], v[84:85], 0, v[114:115]
	v_pk_fma_f32 v[76:77], v[76:77], v[88:89], v[88:89] op_sel_hi:[1,0,0]
	v_pk_fma_f32 v[78:79], v[78:79], v[88:89], v[88:89] op_sel_hi:[1,0,0]
	global_store_dwordx4 v[84:85], v[80:83], off
	v_rcp_f32_e32 v78, v78
	v_rcp_f32_e32 v76, v76
	v_pk_fma_f32 v[80:81], v[90:91], v[88:89], v[88:89] op_sel_hi:[1,0,0]
	v_pk_fma_f32 v[82:83], v[92:93], v[88:89], v[88:89] op_sel_hi:[1,0,0]
	v_rcp_f32_e32 v77, v77
	v_rcp_f32_e32 v79, v79
	v_rcp_f32_e32 v82, v82
	v_rcp_f32_e32 v83, v83
	v_rcp_f32_e32 v80, v80
	v_rcp_f32_e32 v81, v81
	v_pk_mul_f32 v[66:67], v[70:71], v[66:67]
	v_pk_mul_f32 v[64:65], v[68:69], v[64:65]
	v_pk_mul_f32 v[68:69], v[66:67], v[76:77]
	v_pk_mul_f32 v[66:67], v[64:65], v[78:79]
	v_pk_mul_f32 v[74:75], v[74:75], v[80:81]
	v_pk_mul_f32 v[72:73], v[72:73], v[82:83]
	v_pk_mul_f32 v[58:59], v[62:63], v[58:59]
	v_cvt_pk_bf16_f32 v64, v72, v73
	v_cvt_pk_bf16_f32 v65, v74, v75
	v_cvt_pk_bf16_f32 v66, v66, v67
	v_cvt_pk_bf16_f32 v67, v68, v69
	v_mad_u64_u32 v[68:69], s[52:53], v156, s27, v[112:113]
	v_mul_f32_e32 v70, 0xbfb8aa3b, v162
	v_mul_f32_e32 v71, v162, v162
	v_pk_mul_f32 v[74:75], v[62:63], v[70:71] op_sel_hi:[1,0]
	v_pk_mul_f32 v[76:77], v[60:61], v[70:71] op_sel_hi:[1,0]
	v_pk_mul_f32 v[56:57], v[60:61], v[56:57]
	v_pk_mul_f32 v[60:61], v[54:55], v[70:71] op_sel_hi:[1,0]
	v_pk_mul_f32 v[62:63], v[52:53], v[70:71] op_sel_hi:[1,0]
	v_rcp_f32_e32 v72, v71
	v_exp_f32_e32 v62, v62
	v_exp_f32_e32 v60, v60
	v_exp_f32_e32 v61, v61
	v_exp_f32_e32 v63, v63
	v_exp_f32_e32 v76, v76
	v_exp_f32_e32 v74, v74
	v_exp_f32_e32 v75, v75
	v_exp_f32_e32 v77, v77
	v_lshl_add_u64 v[68:69], v[68:69], 0, v[114:115]
	v_pk_fma_f32 v[60:61], v[60:61], v[72:73], v[72:73] op_sel_hi:[1,0,0]
	v_pk_fma_f32 v[62:63], v[62:63], v[72:73], v[72:73] op_sel_hi:[1,0,0]
	global_store_dwordx4 v[68:69], v[64:67], off
	v_rcp_f32_e32 v62, v62
	v_rcp_f32_e32 v60, v60
	v_pk_fma_f32 v[64:65], v[74:75], v[72:73], v[72:73] op_sel_hi:[1,0,0]
	v_pk_fma_f32 v[66:67], v[76:77], v[72:73], v[72:73] op_sel_hi:[1,0,0]
	v_rcp_f32_e32 v61, v61
	v_rcp_f32_e32 v63, v63
	v_rcp_f32_e32 v66, v66
	v_rcp_f32_e32 v67, v67
	v_rcp_f32_e32 v64, v64
	v_rcp_f32_e32 v65, v65
	v_pk_mul_f32 v[50:51], v[54:55], v[50:51]
	v_pk_mul_f32 v[48:49], v[52:53], v[48:49]
	v_pk_mul_f32 v[52:53], v[50:51], v[60:61]
	v_pk_mul_f32 v[50:51], v[48:49], v[62:63]
	v_pk_mul_f32 v[58:59], v[58:59], v[64:65]
	v_pk_mul_f32 v[56:57], v[56:57], v[66:67]
	v_pk_mul_f32 v[42:43], v[46:47], v[42:43]
	v_cvt_pk_bf16_f32 v48, v56, v57
	v_cvt_pk_bf16_f32 v49, v58, v59
	v_cvt_pk_bf16_f32 v50, v50, v51
	v_cvt_pk_bf16_f32 v51, v52, v53
	v_mad_u64_u32 v[52:53], s[52:53], v128, s27, v[112:113]
	v_mov_b32_e32 v54, v53
	v_mad_u64_u32 v[54:55], s[52:53], v129, s27, v[54:55]
	v_mov_b32_e32 v53, v54
	v_mul_f32_e32 v54, 0xbfb8aa3b, v163
	v_mul_f32_e32 v55, v163, v163
	v_pk_mul_f32 v[58:59], v[46:47], v[54:55] op_sel_hi:[1,0]
	v_pk_mul_f32 v[60:61], v[44:45], v[54:55] op_sel_hi:[1,0]
	v_pk_mul_f32 v[40:41], v[44:45], v[40:41]
	v_pk_mul_f32 v[44:45], v[38:39], v[54:55] op_sel_hi:[1,0]
	v_pk_mul_f32 v[46:47], v[36:37], v[54:55] op_sel_hi:[1,0]
	v_rcp_f32_e32 v56, v55
	v_exp_f32_e32 v46, v46
	v_exp_f32_e32 v44, v44
	v_exp_f32_e32 v45, v45
	v_exp_f32_e32 v47, v47
	v_exp_f32_e32 v60, v60
	v_exp_f32_e32 v58, v58
	v_exp_f32_e32 v59, v59
	v_exp_f32_e32 v61, v61
	v_lshl_add_u64 v[52:53], v[52:53], 0, v[114:115]
	v_pk_fma_f32 v[44:45], v[44:45], v[56:57], v[56:57] op_sel_hi:[1,0,0]
	v_pk_fma_f32 v[46:47], v[46:47], v[56:57], v[56:57] op_sel_hi:[1,0,0]
	global_store_dwordx4 v[52:53], v[48:51], off
	v_rcp_f32_e32 v46, v46
	v_rcp_f32_e32 v44, v44
	v_pk_fma_f32 v[48:49], v[58:59], v[56:57], v[56:57] op_sel_hi:[1,0,0]
	v_pk_fma_f32 v[50:51], v[60:61], v[56:57], v[56:57] op_sel_hi:[1,0,0]
	v_rcp_f32_e32 v45, v45
	v_rcp_f32_e32 v47, v47
	v_rcp_f32_e32 v50, v50
	v_rcp_f32_e32 v51, v51
	v_rcp_f32_e32 v48, v48
	v_rcp_f32_e32 v49, v49
	v_pk_mul_f32 v[34:35], v[38:39], v[34:35]
	v_pk_mul_f32 v[32:33], v[36:37], v[32:33]
	v_pk_mul_f32 v[36:37], v[34:35], v[44:45]
	v_pk_mul_f32 v[34:35], v[32:33], v[46:47]
	v_add_u32_e32 v38, 16, v154
	v_pk_mul_f32 v[42:43], v[42:43], v[48:49]
	v_pk_mul_f32 v[40:41], v[40:41], v[50:51]
	v_mul_f32_e32 v39, v132, v132
	v_cvt_pk_bf16_f32 v32, v40, v41
	v_cvt_pk_bf16_f32 v33, v42, v43
	v_cvt_pk_bf16_f32 v34, v34, v35
	v_cvt_pk_bf16_f32 v35, v36, v37
	v_mad_i64_i32 v[36:37], s[52:53], v38, s27, v[112:113]
	v_mul_f32_e32 v38, 0xbfb8aa3b, v132
	v_pk_mul_f32 v[42:43], v[30:31], v[38:39] op_sel_hi:[1,0]
	v_pk_mul_f32 v[44:45], v[28:29], v[38:39] op_sel_hi:[1,0]
	v_pk_mul_f32 v[26:27], v[30:31], v[26:27]
	v_pk_mul_f32 v[24:25], v[28:29], v[24:25]
	v_pk_mul_f32 v[28:29], v[22:23], v[38:39] op_sel_hi:[1,0]
	v_pk_mul_f32 v[30:31], v[20:21], v[38:39] op_sel_hi:[1,0]
	v_rcp_f32_e32 v40, v39
	v_exp_f32_e32 v30, v30
	v_exp_f32_e32 v28, v28
	v_exp_f32_e32 v29, v29
	v_exp_f32_e32 v31, v31
	v_exp_f32_e32 v44, v44
	v_exp_f32_e32 v42, v42
	v_exp_f32_e32 v43, v43
	v_exp_f32_e32 v45, v45
	v_lshl_add_u64 v[36:37], v[36:37], 0, v[114:115]
	v_pk_fma_f32 v[28:29], v[28:29], v[40:41], v[40:41] op_sel_hi:[1,0,0]
	v_pk_fma_f32 v[30:31], v[30:31], v[40:41], v[40:41] op_sel_hi:[1,0,0]
	global_store_dwordx4 v[36:37], v[32:35], off
	v_rcp_f32_e32 v30, v30
	v_rcp_f32_e32 v28, v28
	v_pk_fma_f32 v[32:33], v[42:43], v[40:41], v[40:41] op_sel_hi:[1,0,0]
	v_pk_fma_f32 v[34:35], v[44:45], v[40:41], v[40:41] op_sel_hi:[1,0,0]
	v_rcp_f32_e32 v29, v29
	v_rcp_f32_e32 v31, v31
	v_rcp_f32_e32 v34, v34
	v_rcp_f32_e32 v35, v35
	v_rcp_f32_e32 v32, v32
	v_rcp_f32_e32 v33, v33
	v_pk_mul_f32 v[18:19], v[22:23], v[18:19]
	v_pk_mul_f32 v[16:17], v[20:21], v[16:17]
	v_pk_mul_f32 v[20:21], v[18:19], v[28:29]
	v_pk_mul_f32 v[18:19], v[16:17], v[30:31]
	v_add_u32_e32 v22, 32, v154
	v_pk_mul_f32 v[26:27], v[26:27], v[32:33]
	v_pk_mul_f32 v[24:25], v[24:25], v[34:35]
	v_mul_f32_e32 v23, v133, v133
	v_cvt_pk_bf16_f32 v16, v24, v25
	v_cvt_pk_bf16_f32 v17, v26, v27
	v_cvt_pk_bf16_f32 v18, v18, v19
	v_cvt_pk_bf16_f32 v19, v20, v21
	v_mad_i64_i32 v[20:21], s[52:53], v22, s27, v[112:113]
	v_mul_f32_e32 v22, 0xbfb8aa3b, v133
	v_pk_mul_f32 v[26:27], v[14:15], v[22:23] op_sel_hi:[1,0]
	v_pk_mul_f32 v[28:29], v[12:13], v[22:23] op_sel_hi:[1,0]
	v_pk_mul_f32 v[10:11], v[14:15], v[10:11]
	v_pk_mul_f32 v[8:9], v[12:13], v[8:9]
	v_pk_mul_f32 v[12:13], v[6:7], v[22:23] op_sel_hi:[1,0]
	v_pk_mul_f32 v[14:15], v[4:5], v[22:23] op_sel_hi:[1,0]
	v_rcp_f32_e32 v24, v23
	v_exp_f32_e32 v14, v14
	v_exp_f32_e32 v12, v12
	v_exp_f32_e32 v13, v13
	v_exp_f32_e32 v15, v15
	v_exp_f32_e32 v28, v28
	v_exp_f32_e32 v26, v26
	v_exp_f32_e32 v27, v27
	v_exp_f32_e32 v29, v29
	v_lshl_add_u64 v[20:21], v[20:21], 0, v[114:115]
	v_pk_fma_f32 v[12:13], v[12:13], v[24:25], v[24:25] op_sel_hi:[1,0,0]
	v_pk_fma_f32 v[14:15], v[14:15], v[24:25], v[24:25] op_sel_hi:[1,0,0]
	global_store_dwordx4 v[20:21], v[16:19], off
	v_rcp_f32_e32 v14, v14
	v_rcp_f32_e32 v12, v12
	v_pk_fma_f32 v[16:17], v[26:27], v[24:25], v[24:25] op_sel_hi:[1,0,0]
	v_pk_fma_f32 v[18:19], v[28:29], v[24:25], v[24:25] op_sel_hi:[1,0,0]
	v_rcp_f32_e32 v13, v13
	v_rcp_f32_e32 v15, v15
	v_rcp_f32_e32 v18, v18
	v_rcp_f32_e32 v19, v19
	v_rcp_f32_e32 v16, v16
	v_rcp_f32_e32 v17, v17
	v_pk_mul_f32 v[2:3], v[6:7], v[2:3]
	v_pk_mul_f32 v[0:1], v[4:5], v[0:1]
	v_pk_mul_f32 v[4:5], v[2:3], v[12:13]
	v_pk_mul_f32 v[2:3], v[0:1], v[14:15]
	v_add_u32_e32 v6, 48, v154
	v_pk_mul_f32 v[10:11], v[10:11], v[16:17]
	v_pk_mul_f32 v[8:9], v[8:9], v[18:19]
	s_andn2_b64 vcc, exec, s[6:7]
	v_cvt_pk_bf16_f32 v0, v8, v9
	v_cvt_pk_bf16_f32 v1, v10, v11
	v_cvt_pk_bf16_f32 v2, v2, v3
	v_cvt_pk_bf16_f32 v3, v4, v5
	v_mad_i64_i32 v[4:5], s[52:53], v6, s27, v[112:113]
	v_lshl_add_u64 v[4:5], v[4:5], 0, v[114:115]
	s_mov_b64 s[6:7], -1
	global_store_dwordx4 v[4:5], v[0:3], off
	s_cbranch_vccnz .LBB0_116
	s_andn2_b64 vcc, exec, s[10:11]
	s_cbranch_vccnz .LBB0_115
	s_barrier
	s_branch .LBB0_115

.LBB0_1155:
	s_waitcnt lgkmcnt(0)
	v_mul_f32_e32 v164, 0xbfb8aa3b, v166
	v_mul_f32_e32 v147, v166, v166
	v_pk_mul_f32 v[178:179], v[126:127], v[164:165] op_sel_hi:[1,0]
	v_pk_mul_f32 v[122:123], v[126:127], v[122:123]
	v_pk_mul_f32 v[126:127], v[116:117], v[164:165] op_sel_hi:[1,0]
	v_rcp_f32_e32 v166, v147
	v_pk_mul_f32 v[180:181], v[124:125], v[164:165] op_sel_hi:[1,0]
	v_exp_f32_e32 v126, v126
	v_exp_f32_e32 v127, v127
	v_exp_f32_e32 v180, v180
	v_exp_f32_e32 v178, v178
	v_exp_f32_e32 v179, v179
	v_exp_f32_e32 v181, v181
	v_pk_mul_f32 v[120:121], v[124:125], v[120:121]
	v_pk_mul_f32 v[124:125], v[118:119], v[164:165] op_sel_hi:[1,0]
	v_pk_fma_f32 v[126:127], v[126:127], v[166:167], v[166:167] op_sel_hi:[1,0,0]
	v_exp_f32_e32 v124, v124
	v_exp_f32_e32 v125, v125
	v_pk_fma_f32 v[178:179], v[178:179], v[166:167], v[166:167] op_sel_hi:[1,0,0]
	v_pk_fma_f32 v[180:181], v[180:181], v[166:167], v[166:167] op_sel_hi:[1,0,0]
	v_rcp_f32_e32 v126, v126
	v_rcp_f32_e32 v127, v127
	v_rcp_f32_e32 v180, v180
	v_rcp_f32_e32 v181, v181
	v_rcp_f32_e32 v178, v178
	v_rcp_f32_e32 v179, v179
	v_pk_fma_f32 v[124:125], v[124:125], v[166:167], v[166:167] op_sel_hi:[1,0,0]
	v_pk_mul_f32 v[112:113], v[116:117], v[112:113]
	v_rcp_f32_e32 v124, v124
	v_rcp_f32_e32 v125, v125
	v_pk_mul_f32 v[112:113], v[112:113], v[126:127]
	v_pk_mul_f32 v[122:123], v[122:123], v[178:179]
	v_pk_mul_f32 v[120:121], v[120:121], v[180:181]
	v_pk_mul_f32 v[114:115], v[118:119], v[114:115]
	v_cvt_pk_bf16_f32 v116, v120, v121
	v_cvt_pk_bf16_f32 v117, v122, v123
	v_cvt_pk_bf16_f32 v118, v112, v113
	v_mov_b64_e32 v[112:113], s[64:65]
	v_pk_mul_f32 v[114:115], v[114:115], v[124:125]
	v_mad_u64_u32 v[120:121], s[54:55], v160, s27, v[112:113]
	v_cvt_pk_bf16_f32 v119, v114, v115
	v_mov_b32_e32 v114, v121
	v_mul_f32_e32 v122, 0xbfb8aa3b, v167
	v_mul_f32_e32 v123, v167, v167
	v_mad_u64_u32 v[114:115], s[54:55], v161, s27, v[114:115]
	v_pk_mul_f32 v[126:127], v[110:111], v[122:123] op_sel_hi:[1,0]
	v_pk_mul_f32 v[160:161], v[108:109], v[122:123] op_sel_hi:[1,0]
	v_pk_mul_f32 v[106:107], v[110:111], v[106:107]
	v_pk_mul_f32 v[104:105], v[108:109], v[104:105]
	v_pk_mul_f32 v[108:109], v[102:103], v[122:123] op_sel_hi:[1,0]
	v_pk_mul_f32 v[110:111], v[100:101], v[122:123] op_sel_hi:[1,0]
	v_rcp_f32_e32 v124, v123
	v_exp_f32_e32 v110, v110
	v_exp_f32_e32 v108, v108
	v_exp_f32_e32 v109, v109
	v_exp_f32_e32 v111, v111
	v_lshl_or_b32 v182, s56, 7, v173
	v_exp_f32_e32 v160, v160
	v_exp_f32_e32 v126, v126
	v_exp_f32_e32 v127, v127
	v_exp_f32_e32 v161, v161
	v_ashrrev_i32_e32 v183, 31, v182
	v_mov_b32_e32 v121, v114
	v_lshlrev_b64 v[114:115], 1, v[182:183]
	v_lshl_add_u64 v[120:121], v[120:121], 0, v[114:115]
	v_pk_fma_f32 v[108:109], v[108:109], v[124:125], v[124:125] op_sel_hi:[1,0,0]
	v_pk_fma_f32 v[110:111], v[110:111], v[124:125], v[124:125] op_sel_hi:[1,0,0]
	global_store_dwordx4 v[120:121], v[116:119], off
	v_rcp_f32_e32 v110, v110
	v_rcp_f32_e32 v108, v108
	v_pk_fma_f32 v[116:117], v[126:127], v[124:125], v[124:125] op_sel_hi:[1,0,0]
	v_pk_fma_f32 v[118:119], v[160:161], v[124:125], v[124:125] op_sel_hi:[1,0,0]
	v_rcp_f32_e32 v109, v109
	v_rcp_f32_e32 v111, v111
	v_rcp_f32_e32 v118, v118
	v_rcp_f32_e32 v119, v119
	v_rcp_f32_e32 v116, v116
	v_rcp_f32_e32 v117, v117
	v_pk_mul_f32 v[98:99], v[102:103], v[98:99]
	v_pk_mul_f32 v[96:97], v[100:101], v[96:97]
	v_pk_mul_f32 v[100:101], v[98:99], v[108:109]
	v_pk_mul_f32 v[98:99], v[96:97], v[110:111]
	v_pk_mul_f32 v[106:107], v[106:107], v[116:117]
	v_pk_mul_f32 v[104:105], v[104:105], v[118:119]
	v_pk_mul_f32 v[90:91], v[94:95], v[90:91]
	v_cvt_pk_bf16_f32 v96, v104, v105
	v_cvt_pk_bf16_f32 v97, v106, v107
	v_cvt_pk_bf16_f32 v98, v98, v99
	v_cvt_pk_bf16_f32 v99, v100, v101
	v_mad_u64_u32 v[100:101], s[54:55], v156, s27, v[112:113]
	v_mul_f32_e32 v102, 0xbfb8aa3b, v162
	v_mul_f32_e32 v103, v162, v162
	v_pk_mul_f32 v[106:107], v[94:95], v[102:103] op_sel_hi:[1,0]
	v_pk_mul_f32 v[108:109], v[92:93], v[102:103] op_sel_hi:[1,0]
	v_pk_mul_f32 v[88:89], v[92:93], v[88:89]
	v_pk_mul_f32 v[92:93], v[86:87], v[102:103] op_sel_hi:[1,0]
	v_pk_mul_f32 v[94:95], v[84:85], v[102:103] op_sel_hi:[1,0]
	v_rcp_f32_e32 v104, v103
	v_exp_f32_e32 v94, v94
	v_exp_f32_e32 v92, v92
	v_exp_f32_e32 v93, v93
	v_exp_f32_e32 v95, v95
	v_exp_f32_e32 v108, v108
	v_exp_f32_e32 v106, v106
	v_exp_f32_e32 v107, v107
	v_exp_f32_e32 v109, v109
	v_lshl_add_u64 v[100:101], v[100:101], 0, v[114:115]
	v_pk_fma_f32 v[92:93], v[92:93], v[104:105], v[104:105] op_sel_hi:[1,0,0]
	v_pk_fma_f32 v[94:95], v[94:95], v[104:105], v[104:105] op_sel_hi:[1,0,0]
	global_store_dwordx4 v[100:101], v[96:99], off
	v_rcp_f32_e32 v94, v94
	v_rcp_f32_e32 v92, v92
	v_pk_fma_f32 v[96:97], v[106:107], v[104:105], v[104:105] op_sel_hi:[1,0,0]
	v_pk_fma_f32 v[98:99], v[108:109], v[104:105], v[104:105] op_sel_hi:[1,0,0]
	v_rcp_f32_e32 v93, v93
	v_rcp_f32_e32 v95, v95
	v_rcp_f32_e32 v98, v98
	v_rcp_f32_e32 v99, v99
	v_rcp_f32_e32 v96, v96
	v_rcp_f32_e32 v97, v97
	v_pk_mul_f32 v[82:83], v[86:87], v[82:83]
	v_pk_mul_f32 v[80:81], v[84:85], v[80:81]
	v_pk_mul_f32 v[84:85], v[82:83], v[92:93]
	v_pk_mul_f32 v[82:83], v[80:81], v[94:95]
	v_pk_mul_f32 v[90:91], v[90:91], v[96:97]
	v_pk_mul_f32 v[88:89], v[88:89], v[98:99]
	v_pk_mul_f32 v[74:75], v[78:79], v[74:75]
	v_cvt_pk_bf16_f32 v80, v88, v89
	v_cvt_pk_bf16_f32 v81, v90, v91
	v_cvt_pk_bf16_f32 v82, v82, v83
	v_cvt_pk_bf16_f32 v83, v84, v85
	v_mad_u64_u32 v[84:85], s[54:55], v152, s27, v[112:113]
	v_mul_f32_e32 v86, 0xbfb8aa3b, v163
	v_mul_f32_e32 v87, v163, v163
	v_pk_mul_f32 v[90:91], v[78:79], v[86:87] op_sel_hi:[1,0]
	v_pk_mul_f32 v[92:93], v[76:77], v[86:87] op_sel_hi:[1,0]
	v_pk_mul_f32 v[72:73], v[76:77], v[72:73]
	v_pk_mul_f32 v[76:77], v[70:71], v[86:87] op_sel_hi:[1,0]
	v_pk_mul_f32 v[78:79], v[68:69], v[86:87] op_sel_hi:[1,0]
	v_rcp_f32_e32 v88, v87
	v_exp_f32_e32 v78, v78
	v_exp_f32_e32 v76, v76
	v_exp_f32_e32 v77, v77
	v_exp_f32_e32 v79, v79
	v_exp_f32_e32 v92, v92
	v_exp_f32_e32 v90, v90
	v_exp_f32_e32 v91, v91
	v_exp_f32_e32 v93, v93
	v_lshl_add_u64 v[84:85], v[84:85], 0, v[114:115]
	v_pk_fma_f32 v[76:77], v[76:77], v[88:89], v[88:89] op_sel_hi:[1,0,0]
	v_pk_fma_f32 v[78:79], v[78:79], v[88:89], v[88:89] op_sel_hi:[1,0,0]
	global_store_dwordx4 v[84:85], v[80:83], off
	v_rcp_f32_e32 v78, v78
	v_rcp_f32_e32 v76, v76
	v_pk_fma_f32 v[80:81], v[90:91], v[88:89], v[88:89] op_sel_hi:[1,0,0]
	v_pk_fma_f32 v[82:83], v[92:93], v[88:89], v[88:89] op_sel_hi:[1,0,0]
	v_rcp_f32_e32 v77, v77
	v_rcp_f32_e32 v79, v79
	v_rcp_f32_e32 v82, v82
	v_rcp_f32_e32 v83, v83
	v_rcp_f32_e32 v80, v80
	v_rcp_f32_e32 v81, v81
	v_pk_mul_f32 v[66:67], v[70:71], v[66:67]
	v_pk_mul_f32 v[64:65], v[68:69], v[64:65]
	v_pk_mul_f32 v[68:69], v[66:67], v[76:77]
	v_pk_mul_f32 v[66:67], v[64:65], v[78:79]
	v_pk_mul_f32 v[74:75], v[74:75], v[80:81]
	v_pk_mul_f32 v[72:73], v[72:73], v[82:83]
	v_pk_mul_f32 v[58:59], v[62:63], v[58:59]
	v_cvt_pk_bf16_f32 v64, v72, v73
	v_cvt_pk_bf16_f32 v65, v74, v75
	v_cvt_pk_bf16_f32 v66, v66, v67
	v_cvt_pk_bf16_f32 v67, v68, v69
	v_mad_u64_u32 v[68:69], s[54:55], v150, s27, v[112:113]
	v_mul_f32_e32 v70, 0xbfb8aa3b, v154
	v_mul_f32_e32 v71, v154, v154
	v_pk_mul_f32 v[74:75], v[62:63], v[70:71] op_sel_hi:[1,0]
	v_pk_mul_f32 v[76:77], v[60:61], v[70:71] op_sel_hi:[1,0]
	v_pk_mul_f32 v[56:57], v[60:61], v[56:57]
	v_pk_mul_f32 v[60:61], v[54:55], v[70:71] op_sel_hi:[1,0]
	v_pk_mul_f32 v[62:63], v[52:53], v[70:71] op_sel_hi:[1,0]
	v_rcp_f32_e32 v72, v71
	v_exp_f32_e32 v62, v62
	v_exp_f32_e32 v60, v60
	v_exp_f32_e32 v61, v61
	v_exp_f32_e32 v63, v63
	v_exp_f32_e32 v76, v76
	v_exp_f32_e32 v74, v74
	v_exp_f32_e32 v75, v75
	v_exp_f32_e32 v77, v77
	v_lshl_add_u64 v[68:69], v[68:69], 0, v[114:115]
	v_pk_fma_f32 v[60:61], v[60:61], v[72:73], v[72:73] op_sel_hi:[1,0,0]
	v_pk_fma_f32 v[62:63], v[62:63], v[72:73], v[72:73] op_sel_hi:[1,0,0]
	global_store_dwordx4 v[68:69], v[64:67], off
	v_rcp_f32_e32 v62, v62
	v_rcp_f32_e32 v60, v60
	v_pk_fma_f32 v[64:65], v[74:75], v[72:73], v[72:73] op_sel_hi:[1,0,0]
	v_pk_fma_f32 v[66:67], v[76:77], v[72:73], v[72:73] op_sel_hi:[1,0,0]
	v_rcp_f32_e32 v61, v61
	v_rcp_f32_e32 v63, v63
	v_rcp_f32_e32 v66, v66
	v_rcp_f32_e32 v67, v67
	v_rcp_f32_e32 v64, v64
	v_rcp_f32_e32 v65, v65
	v_pk_mul_f32 v[50:51], v[54:55], v[50:51]
	v_pk_mul_f32 v[48:49], v[52:53], v[48:49]
	v_pk_mul_f32 v[52:53], v[50:51], v[60:61]
	v_pk_mul_f32 v[50:51], v[48:49], v[62:63]
	v_pk_mul_f32 v[58:59], v[58:59], v[64:65]
	v_pk_mul_f32 v[56:57], v[56:57], v[66:67]
	v_pk_mul_f32 v[42:43], v[46:47], v[42:43]
	v_cvt_pk_bf16_f32 v48, v56, v57
	v_cvt_pk_bf16_f32 v49, v58, v59
	v_cvt_pk_bf16_f32 v50, v50, v51
	v_cvt_pk_bf16_f32 v51, v52, v53
	v_mad_u64_u32 v[52:53], s[54:55], v158, s27, v[112:113]
	v_mov_b32_e32 v54, v53
	v_mad_u64_u32 v[54:55], s[54:55], v159, s27, v[54:55]
	v_mov_b32_e32 v53, v54
	v_mul_f32_e32 v54, 0xbfb8aa3b, v155
	v_mul_f32_e32 v55, v155, v155
	v_pk_mul_f32 v[58:59], v[46:47], v[54:55] op_sel_hi:[1,0]
	v_pk_mul_f32 v[60:61], v[44:45], v[54:55] op_sel_hi:[1,0]
	v_pk_mul_f32 v[40:41], v[44:45], v[40:41]
	v_pk_mul_f32 v[44:45], v[38:39], v[54:55] op_sel_hi:[1,0]
	v_pk_mul_f32 v[46:47], v[36:37], v[54:55] op_sel_hi:[1,0]
	v_rcp_f32_e32 v56, v55
	v_exp_f32_e32 v46, v46
	v_exp_f32_e32 v44, v44
	v_exp_f32_e32 v45, v45
	v_exp_f32_e32 v47, v47
	v_exp_f32_e32 v60, v60
	v_exp_f32_e32 v58, v58
	v_exp_f32_e32 v59, v59
	v_exp_f32_e32 v61, v61
	v_lshl_add_u64 v[52:53], v[52:53], 0, v[114:115]
	v_pk_fma_f32 v[44:45], v[44:45], v[56:57], v[56:57] op_sel_hi:[1,0,0]
	v_pk_fma_f32 v[46:47], v[46:47], v[56:57], v[56:57] op_sel_hi:[1,0,0]
	global_store_dwordx4 v[52:53], v[48:51], off
	v_rcp_f32_e32 v46, v46
	v_rcp_f32_e32 v44, v44
	v_pk_fma_f32 v[48:49], v[58:59], v[56:57], v[56:57] op_sel_hi:[1,0,0]
	v_pk_fma_f32 v[50:51], v[60:61], v[56:57], v[56:57] op_sel_hi:[1,0,0]
	v_rcp_f32_e32 v45, v45
	v_rcp_f32_e32 v47, v47
	v_rcp_f32_e32 v50, v50
	v_rcp_f32_e32 v51, v51
	v_rcp_f32_e32 v48, v48
	v_rcp_f32_e32 v49, v49
	v_pk_mul_f32 v[34:35], v[38:39], v[34:35]
	v_pk_mul_f32 v[32:33], v[36:37], v[32:33]
	v_pk_mul_f32 v[36:37], v[34:35], v[44:45]
	v_pk_mul_f32 v[34:35], v[32:33], v[46:47]
	v_add_u32_e32 v38, 16, v146
	v_pk_mul_f32 v[42:43], v[42:43], v[48:49]
	v_pk_mul_f32 v[40:41], v[40:41], v[50:51]
	v_mul_f32_e32 v39, v148, v148
	v_cvt_pk_bf16_f32 v32, v40, v41
	v_cvt_pk_bf16_f32 v33, v42, v43
	v_cvt_pk_bf16_f32 v34, v34, v35
	v_cvt_pk_bf16_f32 v35, v36, v37
	v_mad_i64_i32 v[36:37], s[54:55], v38, s27, v[112:113]
	v_mul_f32_e32 v38, 0xbfb8aa3b, v148
	v_pk_mul_f32 v[42:43], v[30:31], v[38:39] op_sel_hi:[1,0]
	v_pk_mul_f32 v[44:45], v[28:29], v[38:39] op_sel_hi:[1,0]
	v_pk_mul_f32 v[26:27], v[30:31], v[26:27]
	v_pk_mul_f32 v[24:25], v[28:29], v[24:25]
	v_pk_mul_f32 v[28:29], v[22:23], v[38:39] op_sel_hi:[1,0]
	v_pk_mul_f32 v[30:31], v[20:21], v[38:39] op_sel_hi:[1,0]
	v_rcp_f32_e32 v40, v39
	v_exp_f32_e32 v30, v30
	v_exp_f32_e32 v28, v28
	v_exp_f32_e32 v29, v29
	v_exp_f32_e32 v31, v31
	v_exp_f32_e32 v44, v44
	v_exp_f32_e32 v42, v42
	v_exp_f32_e32 v43, v43
	v_exp_f32_e32 v45, v45
	v_lshl_add_u64 v[36:37], v[36:37], 0, v[114:115]
	v_pk_fma_f32 v[28:29], v[28:29], v[40:41], v[40:41] op_sel_hi:[1,0,0]
	v_pk_fma_f32 v[30:31], v[30:31], v[40:41], v[40:41] op_sel_hi:[1,0,0]
	global_store_dwordx4 v[36:37], v[32:35], off
	v_rcp_f32_e32 v30, v30
	v_rcp_f32_e32 v28, v28
	v_pk_fma_f32 v[32:33], v[42:43], v[40:41], v[40:41] op_sel_hi:[1,0,0]
	v_pk_fma_f32 v[34:35], v[44:45], v[40:41], v[40:41] op_sel_hi:[1,0,0]
	v_rcp_f32_e32 v29, v29
	v_rcp_f32_e32 v31, v31
	v_rcp_f32_e32 v34, v34
	v_rcp_f32_e32 v35, v35
	v_rcp_f32_e32 v32, v32
	v_rcp_f32_e32 v33, v33
	v_pk_mul_f32 v[18:19], v[22:23], v[18:19]
	v_pk_mul_f32 v[16:17], v[20:21], v[16:17]
	v_pk_mul_f32 v[20:21], v[18:19], v[28:29]
	v_pk_mul_f32 v[18:19], v[16:17], v[30:31]
	v_add_u32_e32 v22, 32, v146
	v_pk_mul_f32 v[26:27], v[26:27], v[32:33]
	v_pk_mul_f32 v[24:25], v[24:25], v[34:35]
	v_mul_f32_e32 v23, v149, v149
	v_cvt_pk_bf16_f32 v16, v24, v25
	v_cvt_pk_bf16_f32 v17, v26, v27
	v_cvt_pk_bf16_f32 v18, v18, v19
	v_cvt_pk_bf16_f32 v19, v20, v21
	v_mad_i64_i32 v[20:21], s[54:55], v22, s27, v[112:113]
	v_mul_f32_e32 v22, 0xbfb8aa3b, v149
	v_pk_mul_f32 v[26:27], v[14:15], v[22:23] op_sel_hi:[1,0]
	v_pk_mul_f32 v[28:29], v[12:13], v[22:23] op_sel_hi:[1,0]
	v_pk_mul_f32 v[10:11], v[14:15], v[10:11]
	v_pk_mul_f32 v[8:9], v[12:13], v[8:9]
	v_pk_mul_f32 v[12:13], v[6:7], v[22:23] op_sel_hi:[1,0]
	v_pk_mul_f32 v[14:15], v[4:5], v[22:23] op_sel_hi:[1,0]
	v_rcp_f32_e32 v24, v23
	v_exp_f32_e32 v14, v14
	v_exp_f32_e32 v12, v12
	v_exp_f32_e32 v13, v13
	v_exp_f32_e32 v15, v15
	v_exp_f32_e32 v28, v28
	v_exp_f32_e32 v26, v26
	v_exp_f32_e32 v27, v27
	v_exp_f32_e32 v29, v29
	v_lshl_add_u64 v[20:21], v[20:21], 0, v[114:115]
	v_pk_fma_f32 v[12:13], v[12:13], v[24:25], v[24:25] op_sel_hi:[1,0,0]
	v_pk_fma_f32 v[14:15], v[14:15], v[24:25], v[24:25] op_sel_hi:[1,0,0]
	global_store_dwordx4 v[20:21], v[16:19], off
	v_rcp_f32_e32 v14, v14
	v_rcp_f32_e32 v12, v12
	v_pk_fma_f32 v[16:17], v[26:27], v[24:25], v[24:25] op_sel_hi:[1,0,0]
	v_pk_fma_f32 v[18:19], v[28:29], v[24:25], v[24:25] op_sel_hi:[1,0,0]
	v_rcp_f32_e32 v13, v13
	v_rcp_f32_e32 v15, v15
	v_rcp_f32_e32 v18, v18
	v_rcp_f32_e32 v19, v19
	v_rcp_f32_e32 v16, v16
	v_rcp_f32_e32 v17, v17
	v_pk_mul_f32 v[2:3], v[6:7], v[2:3]
	v_pk_mul_f32 v[0:1], v[4:5], v[0:1]
	v_pk_mul_f32 v[4:5], v[2:3], v[12:13]
	v_pk_mul_f32 v[2:3], v[0:1], v[14:15]
	v_add_u32_e32 v6, 48, v146
	v_pk_mul_f32 v[10:11], v[10:11], v[16:17]
	v_pk_mul_f32 v[8:9], v[8:9], v[18:19]
	s_andn2_b64 vcc, exec, s[4:5]
	v_cvt_pk_bf16_f32 v0, v8, v9
	v_cvt_pk_bf16_f32 v1, v10, v11
	v_cvt_pk_bf16_f32 v2, v2, v3
	v_cvt_pk_bf16_f32 v3, v4, v5
	v_mad_i64_i32 v[4:5], s[54:55], v6, s27, v[112:113]
	v_lshl_add_u64 v[4:5], v[4:5], 0, v[114:115]
	s_mov_b64 s[4:5], -1
	global_store_dwordx4 v[4:5], v[0:3], off
	s_cbranch_vccnz .LBB0_1144
	s_andn2_b64 vcc, exec, s[8:9]
	s_cbranch_vccnz .LBB0_1143
	s_barrier
	s_branch .LBB0_1143

.LBB0_2199:
	s_waitcnt lgkmcnt(0)
	v_mul_f32_e32 v164, 0xbfb8aa3b, v166
	v_mul_f32_e32 v147, v166, v166
	v_pk_mul_f32 v[178:179], v[126:127], v[164:165] op_sel_hi:[1,0]
	v_pk_mul_f32 v[122:123], v[126:127], v[122:123]
	v_pk_mul_f32 v[126:127], v[116:117], v[164:165] op_sel_hi:[1,0]
	v_rcp_f32_e32 v166, v147
	v_pk_mul_f32 v[180:181], v[124:125], v[164:165] op_sel_hi:[1,0]
	v_exp_f32_e32 v126, v126
	v_exp_f32_e32 v127, v127
	v_exp_f32_e32 v180, v180
	v_exp_f32_e32 v178, v178
	v_exp_f32_e32 v179, v179
	v_exp_f32_e32 v181, v181
	v_pk_mul_f32 v[120:121], v[124:125], v[120:121]
	v_pk_mul_f32 v[124:125], v[118:119], v[164:165] op_sel_hi:[1,0]
	v_pk_fma_f32 v[126:127], v[126:127], v[166:167], v[166:167] op_sel_hi:[1,0,0]
	v_exp_f32_e32 v124, v124
	v_exp_f32_e32 v125, v125
	v_pk_fma_f32 v[178:179], v[178:179], v[166:167], v[166:167] op_sel_hi:[1,0,0]
	v_pk_fma_f32 v[180:181], v[180:181], v[166:167], v[166:167] op_sel_hi:[1,0,0]
	v_rcp_f32_e32 v126, v126
	v_rcp_f32_e32 v127, v127
	v_rcp_f32_e32 v180, v180
	v_rcp_f32_e32 v181, v181
	v_rcp_f32_e32 v178, v178
	v_rcp_f32_e32 v179, v179
	v_pk_fma_f32 v[124:125], v[124:125], v[166:167], v[166:167] op_sel_hi:[1,0,0]
	v_pk_mul_f32 v[112:113], v[116:117], v[112:113]
	v_rcp_f32_e32 v124, v124
	v_rcp_f32_e32 v125, v125
	v_pk_mul_f32 v[112:113], v[112:113], v[126:127]
	v_pk_mul_f32 v[122:123], v[122:123], v[178:179]
	v_pk_mul_f32 v[120:121], v[120:121], v[180:181]
	v_pk_mul_f32 v[114:115], v[118:119], v[114:115]
	v_cvt_pk_bf16_f32 v116, v120, v121
	v_cvt_pk_bf16_f32 v117, v122, v123
	v_cvt_pk_bf16_f32 v118, v112, v113
	v_mov_b64_e32 v[112:113], s[64:65]
	v_pk_mul_f32 v[114:115], v[114:115], v[124:125]
	v_mad_u64_u32 v[120:121], s[52:53], v160, s54, v[112:113]
	v_cvt_pk_bf16_f32 v119, v114, v115
	v_mov_b32_e32 v114, v121
	v_mul_f32_e32 v122, 0xbfb8aa3b, v167
	v_mul_f32_e32 v123, v167, v167
	v_mad_u64_u32 v[114:115], s[52:53], v161, s54, v[114:115]
	v_pk_mul_f32 v[126:127], v[110:111], v[122:123] op_sel_hi:[1,0]
	v_pk_mul_f32 v[160:161], v[108:109], v[122:123] op_sel_hi:[1,0]
	v_pk_mul_f32 v[106:107], v[110:111], v[106:107]
	v_pk_mul_f32 v[104:105], v[108:109], v[104:105]
	v_pk_mul_f32 v[108:109], v[102:103], v[122:123] op_sel_hi:[1,0]
	v_pk_mul_f32 v[110:111], v[100:101], v[122:123] op_sel_hi:[1,0]
	v_rcp_f32_e32 v124, v123
	v_exp_f32_e32 v110, v110
	v_exp_f32_e32 v108, v108
	v_exp_f32_e32 v109, v109
	v_exp_f32_e32 v111, v111
	v_lshl_or_b32 v182, s56, 7, v173
	v_exp_f32_e32 v160, v160
	v_exp_f32_e32 v126, v126
	v_exp_f32_e32 v127, v127
	v_exp_f32_e32 v161, v161
	v_ashrrev_i32_e32 v183, 31, v182
	v_mov_b32_e32 v121, v114
	v_lshlrev_b64 v[114:115], 1, v[182:183]
	v_lshl_add_u64 v[120:121], v[120:121], 0, v[114:115]
	v_pk_fma_f32 v[108:109], v[108:109], v[124:125], v[124:125] op_sel_hi:[1,0,0]
	v_pk_fma_f32 v[110:111], v[110:111], v[124:125], v[124:125] op_sel_hi:[1,0,0]
	global_store_dwordx4 v[120:121], v[116:119], off
	v_rcp_f32_e32 v110, v110
	v_rcp_f32_e32 v108, v108
	v_pk_fma_f32 v[116:117], v[126:127], v[124:125], v[124:125] op_sel_hi:[1,0,0]
	v_pk_fma_f32 v[118:119], v[160:161], v[124:125], v[124:125] op_sel_hi:[1,0,0]
	v_rcp_f32_e32 v109, v109
	v_rcp_f32_e32 v111, v111
	v_rcp_f32_e32 v118, v118
	v_rcp_f32_e32 v119, v119
	v_rcp_f32_e32 v116, v116
	v_rcp_f32_e32 v117, v117
	v_pk_mul_f32 v[98:99], v[102:103], v[98:99]
	v_pk_mul_f32 v[96:97], v[100:101], v[96:97]
	v_pk_mul_f32 v[100:101], v[98:99], v[108:109]
	v_pk_mul_f32 v[98:99], v[96:97], v[110:111]
	v_pk_mul_f32 v[106:107], v[106:107], v[116:117]
	v_pk_mul_f32 v[104:105], v[104:105], v[118:119]
	v_pk_mul_f32 v[90:91], v[94:95], v[90:91]
	v_cvt_pk_bf16_f32 v96, v104, v105
	v_cvt_pk_bf16_f32 v97, v106, v107
	v_cvt_pk_bf16_f32 v98, v98, v99
	v_cvt_pk_bf16_f32 v99, v100, v101
	v_mad_u64_u32 v[100:101], s[52:53], v156, s54, v[112:113]
	v_mul_f32_e32 v102, 0xbfb8aa3b, v162
	v_mul_f32_e32 v103, v162, v162
	v_pk_mul_f32 v[106:107], v[94:95], v[102:103] op_sel_hi:[1,0]
	v_pk_mul_f32 v[108:109], v[92:93], v[102:103] op_sel_hi:[1,0]
	v_pk_mul_f32 v[88:89], v[92:93], v[88:89]
	v_pk_mul_f32 v[92:93], v[86:87], v[102:103] op_sel_hi:[1,0]
	v_pk_mul_f32 v[94:95], v[84:85], v[102:103] op_sel_hi:[1,0]
	v_rcp_f32_e32 v104, v103
	v_exp_f32_e32 v94, v94
	v_exp_f32_e32 v92, v92
	v_exp_f32_e32 v93, v93
	v_exp_f32_e32 v95, v95
	v_exp_f32_e32 v108, v108
	v_exp_f32_e32 v106, v106
	v_exp_f32_e32 v107, v107
	v_exp_f32_e32 v109, v109
	v_lshl_add_u64 v[100:101], v[100:101], 0, v[114:115]
	v_pk_fma_f32 v[92:93], v[92:93], v[104:105], v[104:105] op_sel_hi:[1,0,0]
	v_pk_fma_f32 v[94:95], v[94:95], v[104:105], v[104:105] op_sel_hi:[1,0,0]
	global_store_dwordx4 v[100:101], v[96:99], off
	v_rcp_f32_e32 v94, v94
	v_rcp_f32_e32 v92, v92
	v_pk_fma_f32 v[96:97], v[106:107], v[104:105], v[104:105] op_sel_hi:[1,0,0]
	v_pk_fma_f32 v[98:99], v[108:109], v[104:105], v[104:105] op_sel_hi:[1,0,0]
	v_rcp_f32_e32 v93, v93
	v_rcp_f32_e32 v95, v95
	v_rcp_f32_e32 v98, v98
	v_rcp_f32_e32 v99, v99
	v_rcp_f32_e32 v96, v96
	v_rcp_f32_e32 v97, v97
	v_pk_mul_f32 v[82:83], v[86:87], v[82:83]
	v_pk_mul_f32 v[80:81], v[84:85], v[80:81]
	v_pk_mul_f32 v[84:85], v[82:83], v[92:93]
	v_pk_mul_f32 v[82:83], v[80:81], v[94:95]
	v_pk_mul_f32 v[90:91], v[90:91], v[96:97]
	v_pk_mul_f32 v[88:89], v[88:89], v[98:99]
	v_pk_mul_f32 v[74:75], v[78:79], v[74:75]
	v_cvt_pk_bf16_f32 v80, v88, v89
	v_cvt_pk_bf16_f32 v81, v90, v91
	v_cvt_pk_bf16_f32 v82, v82, v83
	v_cvt_pk_bf16_f32 v83, v84, v85
	v_mad_u64_u32 v[84:85], s[52:53], v152, s54, v[112:113]
	v_mul_f32_e32 v86, 0xbfb8aa3b, v163
	v_mul_f32_e32 v87, v163, v163
	v_pk_mul_f32 v[90:91], v[78:79], v[86:87] op_sel_hi:[1,0]
	v_pk_mul_f32 v[92:93], v[76:77], v[86:87] op_sel_hi:[1,0]
	v_pk_mul_f32 v[72:73], v[76:77], v[72:73]
	v_pk_mul_f32 v[76:77], v[70:71], v[86:87] op_sel_hi:[1,0]
	v_pk_mul_f32 v[78:79], v[68:69], v[86:87] op_sel_hi:[1,0]
	v_rcp_f32_e32 v88, v87
	v_exp_f32_e32 v78, v78
	v_exp_f32_e32 v76, v76
	v_exp_f32_e32 v77, v77
	v_exp_f32_e32 v79, v79
	v_exp_f32_e32 v92, v92
	v_exp_f32_e32 v90, v90
	v_exp_f32_e32 v91, v91
	v_exp_f32_e32 v93, v93
	v_lshl_add_u64 v[84:85], v[84:85], 0, v[114:115]
	v_pk_fma_f32 v[76:77], v[76:77], v[88:89], v[88:89] op_sel_hi:[1,0,0]
	v_pk_fma_f32 v[78:79], v[78:79], v[88:89], v[88:89] op_sel_hi:[1,0,0]
	global_store_dwordx4 v[84:85], v[80:83], off
	v_rcp_f32_e32 v78, v78
	v_rcp_f32_e32 v76, v76
	v_pk_fma_f32 v[80:81], v[90:91], v[88:89], v[88:89] op_sel_hi:[1,0,0]
	v_pk_fma_f32 v[82:83], v[92:93], v[88:89], v[88:89] op_sel_hi:[1,0,0]
	v_rcp_f32_e32 v77, v77
	v_rcp_f32_e32 v79, v79
	v_rcp_f32_e32 v82, v82
	v_rcp_f32_e32 v83, v83
	v_rcp_f32_e32 v80, v80
	v_rcp_f32_e32 v81, v81
	v_pk_mul_f32 v[66:67], v[70:71], v[66:67]
	v_pk_mul_f32 v[64:65], v[68:69], v[64:65]
	v_pk_mul_f32 v[68:69], v[66:67], v[76:77]
	v_pk_mul_f32 v[66:67], v[64:65], v[78:79]
	v_pk_mul_f32 v[74:75], v[74:75], v[80:81]
	v_pk_mul_f32 v[72:73], v[72:73], v[82:83]
	v_pk_mul_f32 v[58:59], v[62:63], v[58:59]
	v_cvt_pk_bf16_f32 v64, v72, v73
	v_cvt_pk_bf16_f32 v65, v74, v75
	v_cvt_pk_bf16_f32 v66, v66, v67
	v_cvt_pk_bf16_f32 v67, v68, v69
	v_mad_u64_u32 v[68:69], s[52:53], v150, s54, v[112:113]
	v_mul_f32_e32 v70, 0xbfb8aa3b, v154
	v_mul_f32_e32 v71, v154, v154
	v_pk_mul_f32 v[74:75], v[62:63], v[70:71] op_sel_hi:[1,0]
	v_pk_mul_f32 v[76:77], v[60:61], v[70:71] op_sel_hi:[1,0]
	v_pk_mul_f32 v[56:57], v[60:61], v[56:57]
	v_pk_mul_f32 v[60:61], v[54:55], v[70:71] op_sel_hi:[1,0]
	v_pk_mul_f32 v[62:63], v[52:53], v[70:71] op_sel_hi:[1,0]
	v_rcp_f32_e32 v72, v71
	v_exp_f32_e32 v62, v62
	v_exp_f32_e32 v60, v60
	v_exp_f32_e32 v61, v61
	v_exp_f32_e32 v63, v63
	v_exp_f32_e32 v76, v76
	v_exp_f32_e32 v74, v74
	v_exp_f32_e32 v75, v75
	v_exp_f32_e32 v77, v77
	v_lshl_add_u64 v[68:69], v[68:69], 0, v[114:115]
	v_pk_fma_f32 v[60:61], v[60:61], v[72:73], v[72:73] op_sel_hi:[1,0,0]
	v_pk_fma_f32 v[62:63], v[62:63], v[72:73], v[72:73] op_sel_hi:[1,0,0]
	global_store_dwordx4 v[68:69], v[64:67], off
	v_rcp_f32_e32 v62, v62
	v_rcp_f32_e32 v60, v60
	v_pk_fma_f32 v[64:65], v[74:75], v[72:73], v[72:73] op_sel_hi:[1,0,0]
	v_pk_fma_f32 v[66:67], v[76:77], v[72:73], v[72:73] op_sel_hi:[1,0,0]
	v_rcp_f32_e32 v61, v61
	v_rcp_f32_e32 v63, v63
	v_rcp_f32_e32 v66, v66
	v_rcp_f32_e32 v67, v67
	v_rcp_f32_e32 v64, v64
	v_rcp_f32_e32 v65, v65
	v_pk_mul_f32 v[50:51], v[54:55], v[50:51]
	v_pk_mul_f32 v[48:49], v[52:53], v[48:49]
	v_pk_mul_f32 v[52:53], v[50:51], v[60:61]
	v_pk_mul_f32 v[50:51], v[48:49], v[62:63]
	v_pk_mul_f32 v[58:59], v[58:59], v[64:65]
	v_pk_mul_f32 v[56:57], v[56:57], v[66:67]
	v_pk_mul_f32 v[42:43], v[46:47], v[42:43]
	v_cvt_pk_bf16_f32 v48, v56, v57
	v_cvt_pk_bf16_f32 v49, v58, v59
	v_cvt_pk_bf16_f32 v50, v50, v51
	v_cvt_pk_bf16_f32 v51, v52, v53
	v_mad_u64_u32 v[52:53], s[52:53], v158, s54, v[112:113]
	v_mov_b32_e32 v54, v53
	v_mad_u64_u32 v[54:55], s[52:53], v159, s54, v[54:55]
	v_mov_b32_e32 v53, v54
	v_mul_f32_e32 v54, 0xbfb8aa3b, v155
	v_mul_f32_e32 v55, v155, v155
	v_pk_mul_f32 v[58:59], v[46:47], v[54:55] op_sel_hi:[1,0]
	v_pk_mul_f32 v[60:61], v[44:45], v[54:55] op_sel_hi:[1,0]
	v_pk_mul_f32 v[40:41], v[44:45], v[40:41]
	v_pk_mul_f32 v[44:45], v[38:39], v[54:55] op_sel_hi:[1,0]
	v_pk_mul_f32 v[46:47], v[36:37], v[54:55] op_sel_hi:[1,0]
	v_rcp_f32_e32 v56, v55
	v_exp_f32_e32 v46, v46
	v_exp_f32_e32 v44, v44
	v_exp_f32_e32 v45, v45
	v_exp_f32_e32 v47, v47
	v_exp_f32_e32 v60, v60
	v_exp_f32_e32 v58, v58
	v_exp_f32_e32 v59, v59
	v_exp_f32_e32 v61, v61
	v_lshl_add_u64 v[52:53], v[52:53], 0, v[114:115]
	v_pk_fma_f32 v[44:45], v[44:45], v[56:57], v[56:57] op_sel_hi:[1,0,0]
	v_pk_fma_f32 v[46:47], v[46:47], v[56:57], v[56:57] op_sel_hi:[1,0,0]
	global_store_dwordx4 v[52:53], v[48:51], off
	v_rcp_f32_e32 v46, v46
	v_rcp_f32_e32 v44, v44
	v_pk_fma_f32 v[48:49], v[58:59], v[56:57], v[56:57] op_sel_hi:[1,0,0]
	v_pk_fma_f32 v[50:51], v[60:61], v[56:57], v[56:57] op_sel_hi:[1,0,0]
	v_rcp_f32_e32 v45, v45
	v_rcp_f32_e32 v47, v47
	v_rcp_f32_e32 v50, v50
	v_rcp_f32_e32 v51, v51
	v_rcp_f32_e32 v48, v48
	v_rcp_f32_e32 v49, v49
	v_pk_mul_f32 v[34:35], v[38:39], v[34:35]
	v_pk_mul_f32 v[32:33], v[36:37], v[32:33]
	v_pk_mul_f32 v[36:37], v[34:35], v[44:45]
	v_pk_mul_f32 v[34:35], v[32:33], v[46:47]
	v_add_u32_e32 v38, 16, v146
	v_pk_mul_f32 v[42:43], v[42:43], v[48:49]
	v_pk_mul_f32 v[40:41], v[40:41], v[50:51]
	v_mul_f32_e32 v39, v148, v148
	v_cvt_pk_bf16_f32 v32, v40, v41
	v_cvt_pk_bf16_f32 v33, v42, v43
	v_cvt_pk_bf16_f32 v34, v34, v35
	v_cvt_pk_bf16_f32 v35, v36, v37
	v_mad_i64_i32 v[36:37], s[52:53], v38, s54, v[112:113]
	v_mul_f32_e32 v38, 0xbfb8aa3b, v148
	v_pk_mul_f32 v[42:43], v[30:31], v[38:39] op_sel_hi:[1,0]
	v_pk_mul_f32 v[44:45], v[28:29], v[38:39] op_sel_hi:[1,0]
	v_pk_mul_f32 v[26:27], v[30:31], v[26:27]
	v_pk_mul_f32 v[24:25], v[28:29], v[24:25]
	v_pk_mul_f32 v[28:29], v[22:23], v[38:39] op_sel_hi:[1,0]
	v_pk_mul_f32 v[30:31], v[20:21], v[38:39] op_sel_hi:[1,0]
	v_rcp_f32_e32 v40, v39
	v_exp_f32_e32 v30, v30
	v_exp_f32_e32 v28, v28
	v_exp_f32_e32 v29, v29
	v_exp_f32_e32 v31, v31
	v_exp_f32_e32 v44, v44
	v_exp_f32_e32 v42, v42
	v_exp_f32_e32 v43, v43
	v_exp_f32_e32 v45, v45
	v_lshl_add_u64 v[36:37], v[36:37], 0, v[114:115]
	v_pk_fma_f32 v[28:29], v[28:29], v[40:41], v[40:41] op_sel_hi:[1,0,0]
	v_pk_fma_f32 v[30:31], v[30:31], v[40:41], v[40:41] op_sel_hi:[1,0,0]
	global_store_dwordx4 v[36:37], v[32:35], off
	v_rcp_f32_e32 v30, v30
	v_rcp_f32_e32 v28, v28
	v_pk_fma_f32 v[32:33], v[42:43], v[40:41], v[40:41] op_sel_hi:[1,0,0]
	v_pk_fma_f32 v[34:35], v[44:45], v[40:41], v[40:41] op_sel_hi:[1,0,0]
	v_rcp_f32_e32 v29, v29
	v_rcp_f32_e32 v31, v31
	v_rcp_f32_e32 v34, v34
	v_rcp_f32_e32 v35, v35
	v_rcp_f32_e32 v32, v32
	v_rcp_f32_e32 v33, v33
	v_pk_mul_f32 v[18:19], v[22:23], v[18:19]
	v_pk_mul_f32 v[16:17], v[20:21], v[16:17]
	v_pk_mul_f32 v[20:21], v[18:19], v[28:29]
	v_pk_mul_f32 v[18:19], v[16:17], v[30:31]
	v_add_u32_e32 v22, 32, v146
	v_pk_mul_f32 v[26:27], v[26:27], v[32:33]
	v_pk_mul_f32 v[24:25], v[24:25], v[34:35]
	v_mul_f32_e32 v23, v149, v149
	v_cvt_pk_bf16_f32 v16, v24, v25
	v_cvt_pk_bf16_f32 v17, v26, v27
	v_cvt_pk_bf16_f32 v18, v18, v19
	v_cvt_pk_bf16_f32 v19, v20, v21
	v_mad_i64_i32 v[20:21], s[52:53], v22, s54, v[112:113]
	v_mul_f32_e32 v22, 0xbfb8aa3b, v149
	v_pk_mul_f32 v[26:27], v[14:15], v[22:23] op_sel_hi:[1,0]
	v_pk_mul_f32 v[28:29], v[12:13], v[22:23] op_sel_hi:[1,0]
	v_pk_mul_f32 v[10:11], v[14:15], v[10:11]
	v_pk_mul_f32 v[8:9], v[12:13], v[8:9]
	v_pk_mul_f32 v[12:13], v[6:7], v[22:23] op_sel_hi:[1,0]
	v_pk_mul_f32 v[14:15], v[4:5], v[22:23] op_sel_hi:[1,0]
	v_rcp_f32_e32 v24, v23
	v_exp_f32_e32 v14, v14
	v_exp_f32_e32 v12, v12
	v_exp_f32_e32 v13, v13
	v_exp_f32_e32 v15, v15
	v_exp_f32_e32 v28, v28
	v_exp_f32_e32 v26, v26
	v_exp_f32_e32 v27, v27
	v_exp_f32_e32 v29, v29
	v_lshl_add_u64 v[20:21], v[20:21], 0, v[114:115]
	v_pk_fma_f32 v[12:13], v[12:13], v[24:25], v[24:25] op_sel_hi:[1,0,0]
	v_pk_fma_f32 v[14:15], v[14:15], v[24:25], v[24:25] op_sel_hi:[1,0,0]
	global_store_dwordx4 v[20:21], v[16:19], off
	v_rcp_f32_e32 v14, v14
	v_rcp_f32_e32 v12, v12
	v_pk_fma_f32 v[16:17], v[26:27], v[24:25], v[24:25] op_sel_hi:[1,0,0]
	v_pk_fma_f32 v[18:19], v[28:29], v[24:25], v[24:25] op_sel_hi:[1,0,0]
	v_rcp_f32_e32 v13, v13
	v_rcp_f32_e32 v15, v15
	v_rcp_f32_e32 v18, v18
	v_rcp_f32_e32 v19, v19
	v_rcp_f32_e32 v16, v16
	v_rcp_f32_e32 v17, v17
	v_pk_mul_f32 v[2:3], v[6:7], v[2:3]
	v_pk_mul_f32 v[0:1], v[4:5], v[0:1]
	v_pk_mul_f32 v[4:5], v[2:3], v[12:13]
	v_pk_mul_f32 v[2:3], v[0:1], v[14:15]
	v_add_u32_e32 v6, 48, v146
	v_pk_mul_f32 v[10:11], v[10:11], v[16:17]
	v_pk_mul_f32 v[8:9], v[8:9], v[18:19]
	s_andn2_b64 vcc, exec, s[4:5]
	v_cvt_pk_bf16_f32 v0, v8, v9
	v_cvt_pk_bf16_f32 v1, v10, v11
	v_cvt_pk_bf16_f32 v2, v2, v3
	v_cvt_pk_bf16_f32 v3, v4, v5
	v_mad_i64_i32 v[4:5], s[52:53], v6, s54, v[112:113]
	v_lshl_add_u64 v[4:5], v[4:5], 0, v[114:115]
	s_mov_b64 s[4:5], -1
	global_store_dwordx4 v[4:5], v[0:3], off
	s_cbranch_vccnz .LBB0_2188
	s_andn2_b64 vcc, exec, s[8:9]
	s_cbranch_vccnz .LBB0_2187
	s_barrier
	s_branch .LBB0_2187
